# P2: loop-top waits no longer drain the previous unit's stores; P5/P9: LayerNorm gamma/beta loads hoisted out of the row loop (no vmcnt(0) between row stores)
# speedup vs baseline: 1.0069x; 1.0035x over previous
; #define LAS __attribute__((address_space(3)))
; __device__ __forceinline__ void attn_issue(AttnRegs& R, const AttnUnit& u, int blk, bool with_q, const bf16* qkv, const float* bias2) {
;     const int tid = threadIdx.x, lane = tid & 63, w = tid >> 6;
;     const int L = 4096 >> (2 * u.g), gh = u.g * 8 + u.h;
;     const int ch = tid & 15, r0 = tid >> 4;
;     if (with_q) R.tabv = bias2[gh * 192 + (tid < 192 ? tid : 0)];
;     const size_t rb = (size_t)(u.r * L + blk * 128 + r0) * 128 + ch * 8;
;     const bf16* kp = attn_plane(qkv, 1, u) + rb; const bf16* vp = attn_plane(qkv, 2, u) + rb;
; #pragma unroll
;     for (int j = 0; j < 4; ++j) { R.kr[j] = *(const v4u*)(kp + (size_t)j * 32 * 128); R.vr[j] = *(const v4u*)(vp + (size_t)j * 32 * 128); }
;     if (with_q) {
;         const int qi = 16 * w + (lane & 15), kg = lane >> 4;
;         const bf16* qp = attn_plane(qkv, 0, u) + (size_t)(u.r * L + u.n * 128 + qi) * 128 + 8 * kg;
; #pragma unroll
;         for (int s = 0; s < 4; ++s) R.qf[s] = *(const bf16x8*)(qp + 32 * s);
;     }
; __global__ void __launch_bounds__(NTHREADS, 2) fwd_megakernel(Args args) {
;     ...
;     {
;         constexpr int NUNITS = BATCH * 3 * 8 * 32;
;         const int per = (NUNITS + G - 1) / G;
;         const int u0 = vcu * per, u1 = (u0 + per < NUNITS) ? u0 + per : NUNITS;
;         { const v4u z = {0u, 0u, 0u, 0u}; for (int i = threadIdx.x; i < 8192; i += NTHREADS) *(LAS v4u*)(lds + 16 * i) = z; }
;         asm volatile("s_waitcnt lgkmcnt(0)" ::: "memory"); __builtin_amdgcn_s_barrier(); asm volatile("" ::: "memory");
;         AttnRegs R;
;         if (u0 < u1) { const AttnUnit un = attn_decode(u0);
;             if (un.n > 0) { attn_issue(R, un, un.n - 1, false, PROJ, BIAS2); attn_commit(R, un.n - 1, false, lds); }
;             attn_issue(R, un, un.n, true, PROJ, BIAS2); }
.LBB0_145:
	s_add_u32 s0, s40, 0x3fc00000
	s_addc_u32 s1, s41, 0
	s_add_u32 s33, s40, 0xbc00000
	s_addc_u32 s46, s41, 0
	s_add_u32 s47, s38, 0x8000000
	s_addc_u32 s64, s39, 0
	s_add_i32 s4, s59, s10
	s_or_b32 s4, s4, s6
	s_ashr_i32 s5, s4, 31
	s_lshl_b64 s[4:5], s[4:5], 20
	v_lshrrev_b32_e32 v1, 2, v178
	s_add_u32 s4, s18, s4
	v_and_b32_e32 v33, 0xf0, v1
	s_addc_u32 s5, s19, s5
	v_or_b32_e32 v1, v33, v92
	s_add_i32 s8, s9, s8
	v_add_lshl_u32 v80, s8, v1, 8
	v_mov_b32_e32 v81, 0
	v_lshl_add_u64 v[2:3], s[4:5], 0, v[80:81]
	s_add_i32 s4, s58, s10
	v_lshrrev_b32_e32 v1, 1, v178
	s_ashr_i32 s5, s4, 31
	v_and_b32_e32 v34, 24, v1
	s_lshl_b64 s[4:5], s[4:5], 20
	v_lshlrev_b32_e32 v80, 1, v34
	v_add_u32_e32 v0, s9, v0
	s_add_u32 s4, s18, s4
	v_lshl_add_u64 v[2:3], v[2:3], 0, v[80:81]
	v_lshl_or_b32 v80, v0, 7, v91
	s_addc_u32 s5, s19, s5
	v_lshl_add_u64 v[12:13], v[80:81], 1, s[4:5]
	s_mov_b32 s65, 0x18006000
	v_add_co_u32_e32 v0, vcc, s65, v12
	s_mov_b32 s66, 0xc006000
	s_nop 0
	v_addc_co_u32_e32 v1, vcc, 0, v13, vcc
	global_load_dwordx4 v[48:51], v[2:3], off offset:192
	global_load_dwordx4 v[52:55], v[2:3], off offset:128
	global_load_dwordx4 v[56:59], v[2:3], off offset:64
	global_load_dwordx4 v[60:63], v[2:3], off
	v_add_co_u32_e32 v2, vcc, s66, v12
	s_mov_b32 s67, 0x18004000
	s_nop 0
	v_addc_co_u32_e32 v3, vcc, 0, v13, vcc
	v_add_co_u32_e32 v4, vcc, s67, v12
	s_mov_b32 s68, 0xc004000
	s_nop 0
	v_addc_co_u32_e32 v5, vcc, 0, v13, vcc
	v_add_co_u32_e32 v6, vcc, s68, v12
	s_mov_b32 s69, 0x18002000
	s_nop 0
	v_addc_co_u32_e32 v7, vcc, 0, v13, vcc
	v_add_co_u32_e32 v8, vcc, s69, v12
	s_mov_b32 s70, 0xc002000
	s_nop 0
	v_addc_co_u32_e32 v9, vcc, 0, v13, vcc
	s_lshl_b32 s4, s7, 3
	v_add_co_u32_e32 v10, vcc, s70, v12
	s_or_b32 s4, s4, s6
	s_movk_i32 s5, 0xc0
	v_addc_co_u32_e32 v11, vcc, 0, v13, vcc
	s_brev_b32 s71, 24
	s_mul_i32 s6, s4, 0xc0
	v_cmp_gt_u32_e64 s[4:5], s5, v178
	v_add_co_u32_e32 v14, vcc, s71, v12
	s_nop 0
	v_cndmask_b32_e64 v95, 0, v178, s[4:5]
	v_addc_co_u32_e32 v15, vcc, 0, v13, vcc
	s_brev_b32 s72, 48
	v_add_u32_e32 v36, s6, v95
	v_add_co_u32_e32 v12, vcc, s72, v12
	v_ashrrev_i32_e32 v37, 31, v36
	s_nop 0
	v_addc_co_u32_e32 v13, vcc, 0, v13, vcc
	v_lshl_add_u64 v[36:37], v[36:37], 2, s[56:57]
	global_load_dwordx4 v[28:31], v[0:1], off
	s_nop 0
	global_load_dwordx4 v[0:3], v[2:3], off
	s_nop 0
	global_load_dwordx4 v[16:19], v[4:5], off
	s_nop 0
	global_load_dwordx4 v[4:7], v[6:7], off
	s_nop 0
	global_load_dwordx4 v[20:23], v[8:9], off
	s_nop 0
	global_load_dwordx4 v[8:11], v[10:11], off
	s_nop 0
	global_load_dwordx4 v[24:27], v[14:15], off
	s_nop 0
	global_load_dwordx4 v[12:15], v[12:13], off
	v_lshlrev_b32_e32 v35, 2, v178
	global_load_dword v125, v[36:37], off
	s_add_i32 s6, 0, 0x20000
	v_add_u32_e32 v97, s6, v35
	v_and_b32_e32 v102, 12, v35
	v_lshrrev_b32_e32 v35, 1, v92
	v_bfe_u32 v99, v178, 4, 2
	v_and_b32_e32 v35, 2, v35
	v_or_b32_e32 v98, v33, v92
	v_lshrrev_b32_e32 v33, 2, v92
	v_bitop3_b32 v36, v35, v99, v102 bitop3:0x36
	v_or_b32_e32 v104, 4, v99
	v_lshlrev_b32_e32 v100, 3, v33
	v_lshlrev_b32_e32 v103, 4, v36
	v_bitop3_b32 v36, v35, v104, v102 bitop3:0x36
	v_or_b32_e32 v106, 8, v99
	v_or_b32_e32 v108, 12, v99
	v_lshl_or_b32 v111, v99, 3, v33
	v_lshlrev_b32_e32 v33, 1, v90
	v_lshlrev_b32_e32 v105, 4, v36
	v_bitop3_b32 v36, v35, v106, v102 bitop3:0x36
	v_bitop3_b32 v35, v35, v108, v102 bitop3:0x36
	v_and_b32_e32 v113, 12, v178
	v_and_b32_e32 v33, 2, v33
	v_lshlrev_b32_e32 v109, 4, v35
	v_bfe_u32 v112, v178, 1, 1
	v_or_b32_e32 v35, v33, v113
	v_and_b32_e32 v114, 8, v32
	v_or_b32_e32 v32, v35, v112
	v_or_b32_e32 v116, 2, v112
	v_lshlrev_b32_e32 v115, 4, v32
	v_bitop3_b32 v32, v33, v116, v113 bitop3:0x36
	v_or_b32_e32 v118, 4, v112
	v_lshlrev_b32_e32 v117, 4, v32
	v_bitop3_b32 v32, v33, v118, v113 bitop3:0x36
	v_or_b32_e32 v120, 6, v112
	v_lshlrev_b32_e32 v119, 4, v32
	v_bitop3_b32 v32, v33, v120, v113 bitop3:0x36
	v_or_b32_e32 v122, 8, v112
	v_lshlrev_b32_e32 v121, 4, v32
	v_bitop3_b32 v32, v33, v122, v113 bitop3:0x36
	v_or_b32_e32 v124, 10, v112
	v_lshlrev_b32_e32 v123, 4, v32
	v_bitop3_b32 v32, v33, v124, v113 bitop3:0x36
	v_or_b32_e32 v127, 12, v112
	v_lshlrev_b32_e32 v126, 4, v32
	v_bitop3_b32 v32, v33, v127, v113 bitop3:0x36
	v_or_b32_e32 v129, 14, v112
	v_lshlrev_b32_e32 v128, 4, v32
	v_bitop3_b32 v32, v33, v129, v113 bitop3:0x36
	v_lshlrev_b32_e32 v130, 4, v32
	v_lshlrev_b32_e32 v32, 2, v99
	v_lshlrev_b32_e32 v84, 1, v32
	v_mbcnt_lo_u32_b32 v32, -1, 0
	s_mov_b32 s9, 0
	v_or_b32_e32 v96, 0x4000, v93
	v_and_b32_e32 v101, 3, v178
	v_lshlrev_b32_e32 v107, 4, v36
	v_lshl_add_u32 v110, v99, 5, s6
	v_cmp_eq_u32_e64 s[6:7], 0, v99
	s_add_i32 s73, 0, 0x10000
	v_lshlrev_b32_e32 v82, 1, v34
	s_mov_b32 s74, 0xf149f2ca
	v_mov_b32_e32 v131, 0xf149f2ca
	v_mbcnt_hi_u32_b32 v132, -1, v32
	s_waitcnt vmcnt(0)
	s_branch .LBB0_147

; #define LAS __attribute__((address_space(3)))
; __device__ __forceinline__ void attn_commit(const AttnRegs& R, int blk, bool with_tab, LAS unsigned char* lds) {
;     const int tid = threadIdx.x; const int ch = tid & 15, r0 = tid >> 4;
;     LAS unsigned char* Ks = lds; LAS unsigned char* Vs = lds + 65536; LAS float* tab = (LAS float*)(lds + LDS_TAB);
; #pragma unroll
;     for (int j = 0; j < 4; ++j) { const unsigned row = (blk & 1) * 128 + r0 + 32 * j; *(LAS v4u*)(Ks + off_b(row, ch)) = R.kr[j]; *(LAS v4u*)(Vs + off_b(row, ch)) = R.vr[j]; }
;     if (with_tab && tid < 192) tab[tid] = R.tabv;
; }
; __global__ void __launch_bounds__(NTHREADS, 2) fwd_megakernel(Args args) {
;     ...
;         for (int uid = u0; uid < u1; ++uid) {
;             const AttnUnit u = attn_decode(uid);
;             attn_commit(R, u.n, true, lds);
.LBB0_147:
	s_ashr_i32 s8, s11, 8
	s_mul_hi_i32 s10, s8, 0x55555556
	s_lshr_b32 s30, s10, 31
	s_add_i32 s62, s10, s30
	s_mul_i32 s10, s62, 3
	s_sub_i32 s10, s8, s10
	s_lshl_b32 s8, s10, 1
	s_lshr_b32 s30, 32, s8
	s_and_b32 s63, s11, 31
	s_add_i32 s30, s30, -1
	s_and_b32 s84, s30, s63
	s_lshl_b32 s81, s84, 7
	s_and_b32 s30, s81, 0x80
	v_or_b32_e32 v32, s30, v90
	v_lshlrev_b32_e32 v33, 8, v32
	v_or_b32_e32 v34, v33, v93
	v_add_u32_e32 v35, 0, v34
	v_add_u32_e32 v34, s73, v34
	ds_write_b128 v34, v[24:27]
	v_add_u32_e32 v34, 32, v32
	ds_write_b128 v35, v[12:15]
	v_lshlrev_b32_e32 v35, 8, v34
	v_lshlrev_b32_e32 v34, 2, v34
	v_and_b32_e32 v34, 12, v34
	v_bitop3_b32 v34, v34, v92, v94 bitop3:0x36
	v_lshl_or_b32 v34, v34, 4, v35
	v_add_u32_e32 v35, 0, v34
	v_add_u32_e32 v34, s73, v34
	ds_write_b128 v34, v[20:23]
	v_or_b32_e32 v34, v33, v96
	v_add3_u32 v33, v33, v93, 0
	ds_write_b128 v35, v[8:11]
	ds_write_b128 v33, v[4:7] offset:16384
	v_add_u32_e32 v33, s73, v34
	v_add_u32_e32 v32, 0x60, v32
	ds_write_b128 v33, v[16:19]
	v_lshlrev_b32_e32 v33, 8, v32
	v_lshlrev_b32_e32 v32, 2, v32
	v_and_b32_e32 v32, 12, v32
	v_bitop3_b32 v32, v32, v92, v94 bitop3:0x36
	v_lshl_or_b32 v32, v32, 4, v33
	v_add_u32_e32 v33, 0, v32
	v_add_u32_e32 v32, s73, v32
	ds_write_b128 v33, v[0:3]
	ds_write_b128 v32, v[28:31]
	s_and_saveexec_b64 s[58:59], s[4:5]
	s_cbranch_execz .LBB0_149
	ds_write_b32 v97, v125

; __device__ __forceinline__ unsigned cvtpk(float lo, float hi) { f32x2_t v = {lo, hi}; bf16x2_t b = __builtin_convertvector(v, bf16x2_t); return __builtin_bit_cast(unsigned, b); }
; #define PHASE_IDS() int tid_p = threadIdx.x; asm volatile("" : "+v"(tid_p)); const int lane = tid_p & 63; const int wave_p = __builtin_amdgcn_readfirstlane(tid_p >> 6); \
;     const int gw = vcu * NWAVES + wave_p, NGW = G * NWAVES; const size_t gt = (size_t)bx * NTHREADS + tid_p, NGT = (size_t)G * NTHREADS; (void)lane; (void)gw; (void)NGW; (void)gt; (void)NGT
; __global__ void __launch_bounds__(NTHREADS, 2) fwd_megakernel(Args args) {
;     ...
;     { PHASE_IDS();
;     for (int m = gw; m < MTOK; m += NGW) {
;         float* row = HF + (size_t)m * DM; const float* xr = x + (size_t)m * DM; const bf16* mr = MIXB + (size_t)m * DM; f32x4 v[8]; float s = 0.f;
; #pragma unroll
;         for (int j = 0; j < 8; ++j) { const int c = 4 * (lane + 64 * j); const f32x4 xv = __builtin_nontemporal_load((const f32x4*)(xr + c)); const v2u mv = *(const v2u*)(mr + c);
;             v[j] = xv * ALPHA + (f32x4){bflo(mv.x), bfhi(mv.x), bflo(mv.y), bfhi(mv.y)}; s += (v[j][0] + v[j][1]) + (v[j][2] + v[j][3]); }
;         const float mean = wave_sum(s) * (1.f / DM); float s2 = 0.f;
; #pragma unroll
;         for (int j = 0; j < 8; ++j) { v[j] = v[j] - mean; s2 += (v[j][0] * v[j][0] + v[j][1] * v[j][1]) + (v[j][2] * v[j][2] + v[j][3] * v[j][3]); }
;         const float rstd = 1.f / sqrtf(wave_sum(s2) * (1.f / DM) + LN_EPS);
; #pragma unroll
;         for (int j = 0; j < 8; ++j) { const int c = 4 * (lane + 64 * j); const f32x4 gg = *(const f32x4*)(ln1_g + c), bb = *(const f32x4*)(ln1_b + c);
;             const f32x4 o = v[j] * rstd * gg + bb; *(f32x4*)(row + c) = o;
;             v2u wv; wv.x = cvtpk(o[0], o[1]); wv.y = cvtpk(o[2], o[3]); *(v2u*)(HB + (size_t)m * DM + c) = wv; }
.LBB0_340:
	s_or_b64 exec, exec, s[4:5]
	s_waitcnt lgkmcnt(0)
	v_mov_b32_e32 v0, v178
	s_barrier
	v_mbcnt_lo_u32_b32 v179, -1, 0
	v_readfirstlane_b32 s0, v0
	s_ashr_i32 s4, s0, 6
	s_add_i32 s0, s4, s89
	s_cmpk_gt_i32 s0, 0x7fff
	s_cbranch_scc1 .LBB0_343
	v_mbcnt_hi_u32_b32 v1, -1, v179
	v_and_b32_e32 v2, 64, v1
	v_add_u32_e32 v2, 64, v2
	v_xor_b32_e32 v3, 1, v1
	v_cmp_lt_i32_e32 vcc, v3, v2
	s_ashr_i32 s5, s4, 31
	s_ashr_i32 s6, s89, 31
	v_cndmask_b32_e32 v3, v1, v3, vcc
	v_lshlrev_b32_e32 v54, 2, v3
	v_xor_b32_e32 v3, 2, v1
	v_cmp_lt_i32_e32 vcc, v3, v2
	s_add_u32 s4, s4, s89
	s_addc_u32 s5, s5, s6
	v_cndmask_b32_e32 v3, v1, v3, vcc
	v_lshlrev_b32_e32 v55, 2, v3
	v_xor_b32_e32 v3, 4, v1
	v_cmp_lt_i32_e32 vcc, v3, v2
	s_lshl_b64 s[6:7], s[4:5], 12
	s_ashr_i32 s29, s28, 31
	v_cndmask_b32_e32 v3, v1, v3, vcc
	v_lshlrev_b32_e32 v56, 2, v3
	v_xor_b32_e32 v3, 8, v1
	v_cmp_lt_i32_e32 vcc, v3, v2
	s_lshl_b64 s[4:5], s[4:5], 13
	s_movk_i32 s1, 0x1000
	v_cndmask_b32_e32 v3, v1, v3, vcc
	v_lshlrev_b32_e32 v57, 2, v3
	v_xor_b32_e32 v3, 16, v1
	v_cmp_lt_i32_e32 vcc, v3, v2
	v_mov_b32_e32 v29, s7
	v_mov_b32_e32 v31, s5
	v_cndmask_b32_e32 v3, v1, v3, vcc
	v_lshlrev_b32_e32 v58, 2, v3
	v_xor_b32_e32 v3, 32, v1
	v_cmp_lt_i32_e32 vcc, v3, v2
	s_lshl_b64 s[8:9], s[28:29], 13
	s_mov_b32 s10, 0x3f9837f0
	v_cndmask_b32_e32 v1, v1, v3, vcc
	v_lshlrev_b32_e32 v59, 2, v1
	v_lshlrev_b32_e32 v1, 4, v0
	v_and_b32_e32 v2, 0x3f0, v1
	v_mov_b32_e32 v3, 0
	v_or_b32_e32 v4, 0x1000, v2
	v_mov_b32_e32 v5, v3
	v_lshl_add_u64 v[12:13], s[20:21], 0, v[4:5]
	v_lshl_add_u64 v[14:15], s[22:23], 0, v[4:5]
	v_or_b32_e32 v4, 0x1400, v2
	v_lshl_add_u64 v[8:9], s[20:21], 0, v[2:3]
	v_lshl_add_u64 v[10:11], s[22:23], 0, v[2:3]
	v_lshl_add_u64 v[16:17], s[20:21], 0, v[4:5]
	v_lshl_add_u64 v[18:19], s[22:23], 0, v[4:5]
	v_or_b32_e32 v4, 0x1800, v2
	v_or_b32_e32 v2, 0x1c00, v2
	v_and_b32_e32 v0, 63, v0
	v_lshl_add_u64 v[20:21], s[20:21], 0, v[4:5]
	v_lshl_add_u64 v[22:23], s[22:23], 0, v[4:5]
	v_lshl_add_u64 v[24:25], s[20:21], 0, v[2:3]
	v_lshl_add_u64 v[26:27], s[22:23], 0, v[2:3]
	v_lshl_or_b32 v28, v0, 3, s6
	s_lshl_b64 s[6:7], s[28:29], 12
	v_lshl_or_b32 v30, v0, 4, s4
	v_mov_b32_e32 v60, 0x3727c5ac
	s_mov_b32 s11, 0xf800000
	v_mov_b32_e32 v61, 0x260
	s_mov_b32 s20, 0x17c00000
	s_mov_b32 s21, 0x7c00000
	s_mov_b32 s22, 0x17c01000
	global_load_dwordx4 v[114:117], v[8:9], off
	global_load_dwordx4 v[118:121], v[10:11], off
	global_load_dwordx4 v[122:125], v[8:9], off offset:1024
	global_load_dwordx4 v[126:129], v[10:11], off offset:1024
	global_load_dwordx4 v[130:133], v[8:9], off offset:2048
	global_load_dwordx4 v[134:137], v[10:11], off offset:2048
	global_load_dwordx4 v[138:141], v[8:9], off offset:3072
	global_load_dwordx4 v[142:145], v[10:11], off offset:3072
	global_load_dwordx4 v[146:149], v[12:13], off
	global_load_dwordx4 v[150:153], v[14:15], off
	global_load_dwordx4 v[154:157], v[12:13], off offset:1024
	global_load_dwordx4 v[158:161], v[14:15], off offset:1024
	global_load_dwordx4 v[162:165], v[12:13], off offset:2048
	global_load_dwordx4 v[166:169], v[14:15], off offset:2048
	global_load_dwordx4 v[170:173], v[12:13], off offset:3072
	global_load_dwordx4 v[174:177], v[14:15], off offset:3072
	s_waitcnt vmcnt(0)
.LBB0_342:
	v_lshl_add_u64 v[32:33], s[12:13], 0, v[30:31]
	v_add_co_u32_e64 v78, s[4:5], s1, v32
	v_lshl_add_u64 v[48:49], s[40:41], 0, v[30:31]
	s_nop 0
	v_addc_co_u32_e64 v79, s[4:5], 0, v33, s[4:5]
	v_lshl_add_u64 v[36:37], s[40:41], 0, v[28:29]
	global_load_dwordx4 v[38:41], v[32:33], off nt
	global_load_dwordx4 v[42:45], v[32:33], off offset:1024 nt
	global_load_dwordx4 v[50:53], v[32:33], off offset:2048 nt
	global_load_dwordx4 v[62:65], v[32:33], off offset:3072 nt
	v_add_co_u32_e64 v32, s[4:5], s22, v48
	v_add_co_u32_e32 v46, vcc, 0xfc00000, v36
	s_nop 0
	v_addc_co_u32_e64 v33, s[4:5], 0, v49, s[4:5]
	v_add_co_u32_e64 v34, s[4:5], s21, v36
	v_addc_co_u32_e32 v47, vcc, 0, v37, vcc
	s_nop 0
	v_addc_co_u32_e64 v35, s[4:5], 0, v37, s[4:5]
	global_load_dwordx4 v[66:69], v[78:79], off nt
	global_load_dwordx4 v[70:73], v[78:79], off offset:1024 nt
	global_load_dwordx4 v[74:77], v[78:79], off offset:2048 nt
	s_nop 0
	global_load_dwordx4 v[78:81], v[78:79], off offset:3072 nt
	s_nop 0
	global_load_dwordx2 v[36:37], v[46:47], off
	global_load_dwordx2 v[82:83], v[46:47], off offset:512
	global_load_dwordx2 v[84:85], v[46:47], off offset:1024
	global_load_dwordx2 v[86:87], v[46:47], off offset:1536
	global_load_dwordx2 v[88:89], v[46:47], off offset:2048
	global_load_dwordx2 v[90:91], v[46:47], off offset:2560
	global_load_dwordx2 v[92:93], v[46:47], off offset:3072
	s_nop 0
	global_load_dwordx2 v[46:47], v[46:47], off offset:3584
	s_add_i32 s0, s0, s28
	v_lshl_add_u64 v[28:29], v[28:29], 0, s[6:7]
	v_lshl_add_u64 v[30:31], v[30:31], 0, s[8:9]
	s_cmpk_gt_i32 s0, 0x7fff
	s_waitcnt vmcnt(7)
	v_lshlrev_b32_e32 v94, 16, v36
	v_and_b32_e32 v95, 0xffff0000, v36
	v_lshlrev_b32_e32 v36, 16, v37
	v_and_b32_e32 v37, 0xffff0000, v37
	s_waitcnt vmcnt(6)
	v_lshlrev_b32_e32 v96, 16, v82
	v_and_b32_e32 v97, 0xffff0000, v82
	v_lshlrev_b32_e32 v82, 16, v83
	v_and_b32_e32 v83, 0xffff0000, v83
	s_waitcnt vmcnt(5)
	v_lshlrev_b32_e32 v98, 16, v84
	v_and_b32_e32 v99, 0xffff0000, v84
	v_lshlrev_b32_e32 v84, 16, v85
	v_and_b32_e32 v85, 0xffff0000, v85
	s_waitcnt vmcnt(3)
	v_lshlrev_b32_e32 v102, 16, v88
	v_and_b32_e32 v103, 0xffff0000, v88
	v_lshlrev_b32_e32 v88, 16, v89
	v_and_b32_e32 v89, 0xffff0000, v89
	s_waitcnt vmcnt(2)
; __global__ void __launch_bounds__(NTHREADS, 2) fwd_megakernel(Args args) {
;     ...
;         float* row = HF + (size_t)m * DM; const float* xr = x + (size_t)m * DM; const bf16* mr = MIXB + (size_t)m * DM; f32x4 v[8]; float s = 0.f;
; #pragma unroll
;         for (int j = 0; j < 8; ++j) { const int c = 4 * (lane + 64 * j); const f32x4 xv = __builtin_nontemporal_load((const f32x4*)(xr + c)); const v2u mv = *(const v2u*)(mr + c);
;             v[j] = xv * ALPHA + (f32x4){bflo(mv.x), bfhi(mv.x), bflo(mv.y), bfhi(mv.y)}; s += (v[j][0] + v[j][1]) + (v[j][2] + v[j][3]); }
;         const float mean = wave_sum(s) * (1.f / DM); float s2 = 0.f;
; #pragma unroll
;         for (int j = 0; j < 8; ++j) { v[j] = v[j] - mean; s2 += (v[j][0] * v[j][0] + v[j][1] * v[j][1]) + (v[j][2] * v[j][2] + v[j][3] * v[j][3]); }
;         const float rstd = 1.f / sqrtf(wave_sum(s2) * (1.f / DM) + LN_EPS);
	v_lshlrev_b32_e32 v104, 16, v90
	v_and_b32_e32 v105, 0xffff0000, v90
	v_lshlrev_b32_e32 v90, 16, v91
	v_and_b32_e32 v91, 0xffff0000, v91
	v_pk_fma_f32 v[112:113], v[40:41], s[10:11], v[36:37] op_sel_hi:[1,0,1]
	v_pk_fma_f32 v[94:95], v[38:39], s[10:11], v[94:95] op_sel_hi:[1,0,1]
	v_pk_fma_f32 v[82:83], v[44:45], s[10:11], v[82:83] op_sel_hi:[1,0,1]
	v_pk_fma_f32 v[96:97], v[42:43], s[10:11], v[96:97] op_sel_hi:[1,0,1]
	s_waitcnt vmcnt(1)
	v_lshlrev_b32_e32 v106, 16, v92
	v_and_b32_e32 v107, 0xffff0000, v92
	v_lshlrev_b32_e32 v92, 16, v93
	v_and_b32_e32 v93, 0xffff0000, v93
	s_waitcnt vmcnt(0)
	v_lshlrev_b32_e32 v108, 16, v46
	v_and_b32_e32 v109, 0xffff0000, v46
	v_lshlrev_b32_e32 v110, 16, v47
	v_and_b32_e32 v111, 0xffff0000, v47
	v_pk_fma_f32 v[84:85], v[52:53], s[10:11], v[84:85] op_sel_hi:[1,0,1]
	v_pk_fma_f32 v[98:99], v[50:51], s[10:11], v[98:99] op_sel_hi:[1,0,1]
	v_pk_fma_f32 v[52:53], v[68:69], s[10:11], v[88:89] op_sel_hi:[1,0,1]
	v_pk_fma_f32 v[50:51], v[66:67], s[10:11], v[102:103] op_sel_hi:[1,0,1]
	v_pk_fma_f32 v[46:47], v[72:73], s[10:11], v[90:91] op_sel_hi:[1,0,1]
	v_pk_fma_f32 v[44:45], v[70:71], s[10:11], v[104:105] op_sel_hi:[1,0,1]
	v_mov_b32_e32 v66, v94
	v_mov_b32_e32 v67, v96
	v_mov_b32_e32 v68, v95
	v_mov_b32_e32 v69, v97
	v_mov_b32_e32 v70, v112
	v_mov_b32_e32 v71, v82
	v_mov_b32_e32 v72, v113
	v_mov_b32_e32 v73, v83
	v_pk_fma_f32 v[42:43], v[76:77], s[10:11], v[92:93] op_sel_hi:[1,0,1]
	v_pk_fma_f32 v[40:41], v[74:75], s[10:11], v[106:107] op_sel_hi:[1,0,1]
	v_pk_mov_b32 v[74:75], v[98:99], v[84:85] op_sel:[1,0]
	v_mov_b32_e32 v76, v98
	v_mov_b32_e32 v77, v85
	v_pk_add_f32 v[66:67], v[66:67], v[68:69]
	v_pk_add_f32 v[68:69], v[70:71], v[72:73]
	v_lshlrev_b32_e32 v100, 16, v86
	v_and_b32_e32 v101, 0xffff0000, v86
	v_lshlrev_b32_e32 v86, 16, v87
	v_and_b32_e32 v87, 0xffff0000, v87
	v_pk_add_f32 v[70:71], v[74:75], v[76:77]
	v_pk_add_f32 v[66:67], v[66:67], v[68:69]
	v_pk_fma_f32 v[64:65], v[64:65], s[10:11], v[86:87] op_sel_hi:[1,0,1]
	v_pk_fma_f32 v[62:63], v[62:63], s[10:11], v[100:101] op_sel_hi:[1,0,1]
	v_pk_add_f32 v[68:69], v[70:71], v[70:71] op_sel:[0,1] op_sel_hi:[1,0]
	v_add_f32_e32 v66, 0, v66
	v_pk_fma_f32 v[38:39], v[80:81], s[10:11], v[110:111] op_sel_hi:[1,0,1]
	v_pk_fma_f32 v[36:37], v[78:79], s[10:11], v[108:109] op_sel_hi:[1,0,1]
	v_add_f32_e32 v78, v62, v63
	v_add_f32_e32 v80, v64, v65
	v_mov_b32_e32 v87, v50
	v_mov_b32_e32 v79, v52
	v_mov_b32_e32 v81, v53
	v_mov_b32_e32 v69, v51
	v_add_f32_e32 v86, v66, v67
	v_pk_mov_b32 v[88:89], v[44:45], v[46:47] op_sel:[1,0]
	v_mov_b32_e32 v90, v44
	v_mov_b32_e32 v91, v47
	v_pk_add_f32 v[72:73], v[78:79], v[80:81]
	v_pk_add_f32 v[66:67], v[86:87], v[68:69]
	v_pk_add_f32 v[74:75], v[88:89], v[90:91]
	v_pk_add_f32 v[66:67], v[66:67], v[72:73]
	v_pk_add_f32 v[70:71], v[74:75], v[74:75] op_sel:[0,1] op_sel_hi:[1,0]
	v_pk_add_f32 v[66:67], v[66:67], v[66:67] op_sel:[0,1] op_sel_hi:[1,0]
	v_add_f32_e32 v92, v40, v41
	v_add_f32_e32 v100, v42, v43
	v_mov_b32_e32 v93, v38
	v_mov_b32_e32 v101, v39
	v_mov_b32_e32 v71, v37
	v_mov_b32_e32 v67, v36
	v_pk_add_f32 v[76:77], v[92:93], v[100:101]
	v_pk_add_f32 v[66:67], v[66:67], v[70:71]
	s_nop 0
	v_pk_add_f32 v[66:67], v[66:67], v[76:77]
	s_nop 0
	v_add_f32_e32 v66, v66, v67
	ds_bpermute_b32 v67, v54, v66
	s_waitcnt lgkmcnt(0)
	v_add_f32_e32 v66, v66, v67
	ds_bpermute_b32 v67, v55, v66
	s_waitcnt lgkmcnt(0)
	v_add_f32_e32 v66, v66, v67
	ds_bpermute_b32 v67, v56, v66
	s_waitcnt lgkmcnt(0)
	v_add_f32_e32 v66, v66, v67
	ds_bpermute_b32 v67, v57, v66
	s_waitcnt lgkmcnt(0)
	v_add_f32_e32 v66, v66, v67
	ds_bpermute_b32 v67, v58, v66
	s_waitcnt lgkmcnt(0)
	v_add_f32_e32 v66, v66, v67
	ds_bpermute_b32 v67, v59, v66
	s_waitcnt lgkmcnt(0)
	v_add_f32_e32 v66, v66, v67
	v_fmamk_f32 v113, v66, 0xba000000, v113
	v_fmamk_f32 v95, v66, 0xba000000, v95
	v_fmamk_f32 v83, v66, 0xba000000, v83
	v_fmamk_f32 v97, v66, 0xba000000, v97
	v_fmac_f32_e32 v112, 0xba000000, v66
	v_fmac_f32_e32 v94, 0xba000000, v66
	v_fmac_f32_e32 v82, 0xba000000, v66
	v_fmac_f32_e32 v96, 0xba000000, v66
	v_fmamk_f32 v99, v66, 0xba000000, v99
	v_fmac_f32_e32 v98, 0xba000000, v66
	v_fmamk_f32 v85, v66, 0xba000000, v85
	v_fmac_f32_e32 v84, 0xba000000, v66
	v_mov_b32_e32 v68, v95
	v_mov_b32_e32 v69, v97
	v_mov_b32_e32 v72, v113
	v_mov_b32_e32 v73, v83
	v_fmamk_f32 v63, v66, 0xba000000, v63
	v_fmac_f32_e32 v62, 0xba000000, v66
	v_fmamk_f32 v65, v66, 0xba000000, v65
	v_fmac_f32_e32 v64, 0xba000000, v66
	v_fmamk_f32 v53, v66, 0xba000000, v53
	v_fmac_f32_e32 v52, 0xba000000, v66
	v_fmamk_f32 v51, v66, 0xba000000, v51
	v_fmac_f32_e32 v50, 0xba000000, v66
	v_fmamk_f32 v45, v66, 0xba000000, v45
	v_fmac_f32_e32 v44, 0xba000000, v66
	v_fmamk_f32 v47, v66, 0xba000000, v47
	v_fmac_f32_e32 v46, 0xba000000, v66
	v_fmamk_f32 v41, v66, 0xba000000, v41
	v_fmac_f32_e32 v40, 0xba000000, v66
	v_fmamk_f32 v43, v66, 0xba000000, v43
	v_fmac_f32_e32 v42, 0xba000000, v66
	v_fmamk_f32 v39, v66, 0xba000000, v39
	v_fmac_f32_e32 v38, 0xba000000, v66
	v_fmamk_f32 v37, v66, 0xba000000, v37
	v_fmac_f32_e32 v36, 0xba000000, v66
	v_mov_b32_e32 v66, v94
	v_mov_b32_e32 v67, v96
	v_mov_b32_e32 v70, v112
	v_mov_b32_e32 v71, v82
	v_pk_mul_f32 v[74:75], v[84:85], v[84:85]
	v_pk_mul_f32 v[76:77], v[98:99], v[98:99]
	v_pk_mul_f32 v[68:69], v[68:69], v[68:69]
	v_pk_mul_f32 v[72:73], v[72:73], v[72:73]
	v_pk_mov_b32 v[100:101], v[76:77], v[74:75] op_sel:[1,0]
	v_mov_b32_e32 v77, v75
	v_pk_fma_f32 v[66:67], v[66:67], v[66:67], v[68:69]
	v_pk_fma_f32 v[68:69], v[70:71], v[70:71], v[72:73]
	v_mul_f32_e32 v78, v63, v63
	v_mul_f32_e32 v80, v65, v65
	v_pk_add_f32 v[70:71], v[100:101], v[76:77]
	v_pk_add_f32 v[66:67], v[66:67], v[68:69]
; __device__ __forceinline__ unsigned cvtpk(float lo, float hi) { f32x2_t v = {lo, hi}; bf16x2_t b = __builtin_convertvector(v, bf16x2_t); return __builtin_bit_cast(unsigned, b); }
; __global__ void __launch_bounds__(NTHREADS, 2) fwd_megakernel(Args args) {
;     ...
;         const float rstd = 1.f / sqrtf(wave_sum(s2) * (1.f / DM) + LN_EPS);
; #pragma unroll
;         for (int j = 0; j < 8; ++j) { const int c = 4 * (lane + 64 * j); const f32x4 gg = *(const f32x4*)(ln1_g + c), bb = *(const f32x4*)(ln1_b + c);
;             const f32x4 o = v[j] * rstd * gg + bb; *(f32x4*)(row + c) = o;
;             v2u wv; wv.x = cvtpk(o[0], o[1]); wv.y = cvtpk(o[2], o[3]); *(v2u*)(HB + (size_t)m * DM + c) = wv; }
	v_mul_f32_e32 v93, v50, v50
	v_mul_f32_e32 v102, v51, v51
	v_mul_f32_e32 v103, v52, v52
	v_mul_f32_e32 v104, v53, v53
	v_pk_fma_f32 v[74:75], v[62:63], v[62:63], v[78:79] op_sel_hi:[1,1,0]
	v_pk_fma_f32 v[78:79], v[64:65], v[64:65], v[80:81] op_sel_hi:[1,1,0]
	v_pk_add_f32 v[68:69], v[70:71], v[70:71] op_sel:[0,1] op_sel_hi:[1,0]
	v_pk_add_f32 v[66:67], v[66:67], v[66:67] op_sel:[0,1] op_sel_hi:[1,0]
	v_pk_mul_f32 v[86:87], v[46:47], v[46:47]
	v_pk_mul_f32 v[88:89], v[44:45], v[44:45]
	v_mov_b32_e32 v75, v103
	v_mov_b32_e32 v79, v104
	v_mov_b32_e32 v69, v102
	v_mov_b32_e32 v67, v93
	v_pk_mov_b32 v[80:81], v[88:89], v[86:87] op_sel:[1,0]
	v_mov_b32_e32 v89, v87
	v_pk_add_f32 v[70:71], v[74:75], v[78:79]
	v_pk_add_f32 v[66:67], v[66:67], v[68:69]
	v_mul_f32_e32 v90, v41, v41
	v_mul_f32_e32 v92, v43, v43
	v_pk_add_f32 v[72:73], v[80:81], v[88:89]
	v_pk_add_f32 v[66:67], v[66:67], v[70:71]
	v_mul_f32_e32 v105, v36, v36
	v_mul_f32_e32 v106, v37, v37
	v_mul_f32_e32 v107, v38, v38
	v_mul_f32_e32 v108, v39, v39
	v_pk_fma_f32 v[86:87], v[40:41], v[40:41], v[90:91] op_sel_hi:[1,1,0]
	v_pk_fma_f32 v[90:91], v[42:43], v[42:43], v[92:93] op_sel_hi:[1,1,0]
	v_pk_add_f32 v[72:73], v[72:73], v[72:73] op_sel:[0,1] op_sel_hi:[1,0]
	v_pk_add_f32 v[66:67], v[66:67], v[66:67] op_sel:[0,1] op_sel_hi:[1,0]
	v_mov_b32_e32 v87, v107
	v_mov_b32_e32 v91, v108
	v_mov_b32_e32 v73, v106
	v_mov_b32_e32 v67, v105
	v_pk_add_f32 v[74:75], v[86:87], v[90:91]
	v_pk_add_f32 v[66:67], v[66:67], v[72:73]
	s_nop 0
	v_pk_add_f32 v[66:67], v[66:67], v[74:75]
	s_nop 0
	v_add_f32_e32 v66, v66, v67
	ds_bpermute_b32 v67, v54, v66
	s_waitcnt lgkmcnt(0)
	v_add_f32_e32 v66, v66, v67
	ds_bpermute_b32 v67, v55, v66
	s_waitcnt lgkmcnt(0)
	v_add_f32_e32 v66, v66, v67
	ds_bpermute_b32 v67, v56, v66
	s_waitcnt lgkmcnt(0)
	v_add_f32_e32 v66, v66, v67
	ds_bpermute_b32 v67, v57, v66
	s_waitcnt lgkmcnt(0)
	v_add_f32_e32 v66, v66, v67
	ds_bpermute_b32 v67, v58, v66
	s_waitcnt lgkmcnt(0)
	v_add_f32_e32 v66, v66, v67
	ds_bpermute_b32 v67, v59, v66
	s_waitcnt lgkmcnt(0)
	v_add_f32_e32 v66, v66, v67
	v_fmamk_f32 v66, v66, 0x3a000000, v60
	v_mul_f32_e32 v67, 0x4f800000, v66
	v_cmp_gt_f32_e32 vcc, s11, v66
	s_nop 1
	v_cndmask_b32_e32 v66, v66, v67, vcc
	v_sqrt_f32_e32 v67, v66
	s_nop 0
	v_add_u32_e32 v68, -1, v67
	v_add_u32_e32 v69, 1, v67
	v_fma_f32 v70, -v68, v67, v66
	v_fma_f32 v71, -v69, v67, v66
	v_cmp_ge_f32_e64 s[4:5], 0, v70
	s_nop 1
	v_cndmask_b32_e64 v67, v67, v68, s[4:5]
	v_cmp_lt_f32_e64 s[4:5], 0, v71
	s_nop 1
	v_cndmask_b32_e64 v67, v67, v69, s[4:5]
	v_mul_f32_e32 v68, 0x37800000, v67
	v_cndmask_b32_e32 v67, v67, v68, vcc
	v_cmp_class_f32_e32 vcc, v66, v61
	s_nop 1
	v_cndmask_b32_e32 v66, v67, v66, vcc
	v_div_scale_f32 v67, s[4:5], v66, v66, 1.0
	v_rcp_f32_e32 v69, v67
	v_div_scale_f32 v68, vcc, 1.0, v66, 1.0
	v_fma_f32 v70, -v67, v69, 1.0
	v_fmac_f32_e32 v69, v70, v69
	v_mul_f32_e32 v70, v68, v69
	v_fma_f32 v71, -v67, v70, v68
	v_fmac_f32_e32 v70, v71, v69
	v_fma_f32 v67, -v67, v70, v68
	v_div_fmas_f32 v67, v67, v69, v70
	v_div_fixup_f32 v66, v67, v66, 1.0
	v_pk_mul_f32 v[68:69], v[66:67], v[94:95] op_sel_hi:[0,1]
	v_pk_mul_f32 v[70:71], v[66:67], v[112:113] op_sel_hi:[0,1]
	v_pk_fma_f32 v[2:3], v[70:71], v[116:117], v[120:121]
	v_pk_fma_f32 v[0:1], v[68:69], v[114:115], v[118:119]
	global_store_dwordx4 v[32:33], v[0:3], off offset:-4096
	v_add_co_u32_e32 v48, vcc, s20, v48
	s_nop 0
	v_cvt_pk_bf16_f32 v0, v0, v1
	v_cvt_pk_bf16_f32 v1, v2, v3
	global_store_dwordx2 v[34:35], v[0:1], off
	v_pk_mul_f32 v[68:69], v[66:67], v[82:83] op_sel_hi:[0,1]
	v_pk_mul_f32 v[70:71], v[66:67], v[96:97] op_sel_hi:[0,1]
	v_addc_co_u32_e32 v49, vcc, 0, v49, vcc
	v_pk_mul_f32 v[64:65], v[66:67], v[64:65] op_sel_hi:[0,1]
	v_pk_mul_f32 v[62:63], v[66:67], v[62:63] op_sel_hi:[0,1]
	v_pk_mul_f32 v[50:51], v[66:67], v[50:51] op_sel_hi:[0,1]
	v_pk_mul_f32 v[46:47], v[66:67], v[46:47] op_sel_hi:[0,1]
	v_pk_mul_f32 v[44:45], v[66:67], v[44:45] op_sel_hi:[0,1]
	v_pk_mul_f32 v[42:43], v[66:67], v[42:43] op_sel_hi:[0,1]
	v_pk_mul_f32 v[40:41], v[66:67], v[40:41] op_sel_hi:[0,1]
	v_pk_mul_f32 v[38:39], v[66:67], v[38:39] op_sel_hi:[0,1]
	v_pk_mul_f32 v[36:37], v[66:67], v[36:37] op_sel_hi:[0,1]
	v_pk_fma_f32 v[0:1], v[70:71], v[122:123], v[126:127]
	v_pk_fma_f32 v[2:3], v[68:69], v[124:125], v[128:129]
	global_store_dwordx4 v[48:49], v[0:3], off offset:1024
	v_pk_mul_f32 v[68:69], v[66:67], v[84:85] op_sel_hi:[0,1]
	v_pk_mul_f32 v[70:71], v[66:67], v[98:99] op_sel_hi:[0,1]
	v_cvt_pk_bf16_f32 v0, v0, v1
	v_cvt_pk_bf16_f32 v1, v2, v3
	global_store_dwordx2 v[34:35], v[0:1], off offset:512
	v_pk_fma_f32 v[0:1], v[70:71], v[130:131], v[134:135]
	v_pk_fma_f32 v[2:3], v[68:69], v[132:133], v[136:137]
	global_store_dwordx4 v[48:49], v[0:3], off offset:2048
	s_nop 1
	v_cvt_pk_bf16_f32 v0, v0, v1
	v_cvt_pk_bf16_f32 v1, v2, v3
	global_store_dwordx2 v[34:35], v[0:1], off offset:1024
	v_pk_fma_f32 v[0:1], v[62:63], v[138:139], v[142:143]
	v_pk_fma_f32 v[2:3], v[64:65], v[140:141], v[144:145]
	global_store_dwordx4 v[48:49], v[0:3], off offset:3072
	v_pk_mul_f32 v[48:49], v[66:67], v[52:53] op_sel_hi:[0,1]
	s_nop 0
	v_cvt_pk_bf16_f32 v0, v0, v1
	v_cvt_pk_bf16_f32 v1, v2, v3
	global_store_dwordx2 v[34:35], v[0:1], off offset:1536
	v_pk_fma_f32 v[0:1], v[50:51], v[146:147], v[150:151]
	v_pk_fma_f32 v[2:3], v[48:49], v[148:149], v[152:153]
	global_store_dwordx4 v[32:33], v[0:3], off
	s_nop 1
	v_cvt_pk_bf16_f32 v0, v0, v1
	v_cvt_pk_bf16_f32 v1, v2, v3
	global_store_dwordx2 v[34:35], v[0:1], off offset:2048
	v_pk_fma_f32 v[0:1], v[44:45], v[154:155], v[158:159]
	v_pk_fma_f32 v[2:3], v[46:47], v[156:157], v[160:161]
	global_store_dwordx4 v[32:33], v[0:3], off offset:1024
	s_nop 1
	v_cvt_pk_bf16_f32 v0, v0, v1
	v_cvt_pk_bf16_f32 v1, v2, v3
	global_store_dwordx2 v[34:35], v[0:1], off offset:2560
	v_pk_fma_f32 v[0:1], v[40:41], v[162:163], v[166:167]
	v_pk_fma_f32 v[2:3], v[42:43], v[164:165], v[168:169]
	global_store_dwordx4 v[32:33], v[0:3], off offset:2048
	s_nop 1
	v_cvt_pk_bf16_f32 v0, v0, v1
	v_cvt_pk_bf16_f32 v1, v2, v3
	global_store_dwordx2 v[34:35], v[0:1], off offset:3072
	v_pk_fma_f32 v[0:1], v[36:37], v[170:171], v[174:175]
	v_pk_fma_f32 v[2:3], v[38:39], v[172:173], v[176:177]
	global_store_dwordx4 v[32:33], v[0:3], off offset:3072
	s_nop 1
	v_cvt_pk_bf16_f32 v0, v0, v1
	v_cvt_pk_bf16_f32 v1, v2, v3
	global_store_dwordx2 v[34:35], v[0:1], off offset:3584
	s_cbranch_scc0 .LBB0_342

; #define PHASE_IDS() int tid_p = threadIdx.x; asm volatile("" : "+v"(tid_p)); const int lane = tid_p & 63; const int wave_p = __builtin_amdgcn_readfirstlane(tid_p >> 6); \
;     const int gw = vcu * NWAVES + wave_p, NGW = G * NWAVES; const size_t gt = (size_t)bx * NTHREADS + tid_p, NGT = (size_t)G * NTHREADS; (void)lane; (void)gw; (void)NGW; (void)gt; (void)NGT
; __global__ void __launch_bounds__(NTHREADS, 2) fwd_megakernel(Args args) {
;     ...
;     { PHASE_IDS();
;     for (int m = gw; m < MTOK; m += NGW) {
;         const float* row = HF + (size_t)m * DM; const bf16* mr = MIXB + (size_t)m * DM; f32x4 v[8]; float s = 0.f;
; #pragma unroll
;         for (int j = 0; j < 8; ++j) { const int c = 4 * (lane + 64 * j); const f32x4 hv = *(const f32x4*)(row + c); const v2u mv = *(const v2u*)(mr + c);
;             v[j] = hv * ALPHA + (f32x4){bflo(mv.x), bfhi(mv.x), bflo(mv.y), bfhi(mv.y)}; s += (v[j][0] + v[j][1]) + (v[j][2] + v[j][3]); }
;         const float mean = wave_sum(s) * (1.f / DM); float s2 = 0.f;
; #pragma unroll
;         for (int j = 0; j < 8; ++j) { v[j] = v[j] - mean; s2 += (v[j][0] * v[j][0] + v[j][1] * v[j][1]) + (v[j][2] * v[j][2] + v[j][3] * v[j][3]); }
;         const float rstd = 1.f / sqrtf(wave_sum(s2) * (1.f / DM) + LN_EPS);
; #pragma unroll
;         for (int j = 0; j < 8; ++j) { const int c = 4 * (lane + 64 * j); const f32x4 gg = *(const f32x4*)(ln2_g + c), bb = *(const f32x4*)(ln2_b + c);
;             __builtin_nontemporal_store(v[j] * rstd * gg + bb, (f32x4*)(args.out + (size_t)m * DM + c)); }
.LBB0_609:
	s_or_b64 exec, exec, s[2:3]
	s_waitcnt lgkmcnt(0)
	s_barrier
	s_nop 0
	v_readfirstlane_b32 s0, v178
	s_ashr_i32 s0, s0, 6
	s_add_i32 s11, s0, s89
	s_cmpk_gt_i32 s11, 0x7fff
	s_cbranch_scc1 .LBB0_612
	v_mbcnt_hi_u32_b32 v0, -1, v179
	v_and_b32_e32 v1, 64, v0
	v_add_u32_e32 v1, 64, v1
	v_xor_b32_e32 v2, 1, v0
	v_cmp_lt_i32_e32 vcc, v2, v1
	s_ashr_i32 s1, s0, 31
	s_ashr_i32 s2, s89, 31
	v_cndmask_b32_e32 v2, v0, v2, vcc
	v_lshlrev_b32_e32 v52, 2, v2
	v_xor_b32_e32 v2, 2, v0
	v_cmp_lt_i32_e32 vcc, v2, v1
	s_add_u32 s0, s0, s89
	s_addc_u32 s1, s1, s2
	v_cndmask_b32_e32 v2, v0, v2, vcc
	v_lshlrev_b32_e32 v53, 2, v2
	v_xor_b32_e32 v2, 4, v0
	v_cmp_lt_i32_e32 vcc, v2, v1
	v_mov_b32_e32 v9, 0
	s_lshl_b64 s[8:9], s[0:1], 13
	v_cndmask_b32_e32 v2, v0, v2, vcc
	v_lshlrev_b32_e32 v54, 2, v2
	v_xor_b32_e32 v2, 8, v0
	v_cmp_lt_i32_e32 vcc, v2, v1
	s_add_u32 s2, s38, s8
	s_addc_u32 s3, s39, s9
	v_cndmask_b32_e32 v2, v0, v2, vcc
	v_lshlrev_b32_e32 v55, 2, v2
	v_xor_b32_e32 v2, 16, v0
	v_cmp_lt_i32_e32 vcc, v2, v1
	s_ashr_i32 s29, s28, 31
	s_lshl_b64 s[4:5], s[28:29], 13
	v_cndmask_b32_e32 v2, v0, v2, vcc
	v_lshlrev_b32_e32 v56, 2, v2
	v_xor_b32_e32 v2, 32, v0
	v_cmp_lt_i32_e32 vcc, v2, v1
	v_mov_b32_e32 v1, v9
	s_lshl_b64 s[0:1], s[0:1], 12
	v_cndmask_b32_e32 v0, v0, v2, vcc
	v_lshlrev_b32_e32 v57, 2, v0
	v_lshlrev_b32_e32 v0, 4, v178
	v_and_b32_e32 v8, 0x3f0, v0
	v_or_b32_e32 v0, 0x1000, v8
	v_lshl_add_u64 v[14:15], s[48:49], 0, v[0:1]
	v_lshl_add_u64 v[16:17], s[50:51], 0, v[0:1]
	v_or_b32_e32 v0, 0x1400, v8
	v_lshl_add_u64 v[18:19], s[48:49], 0, v[0:1]
	v_lshl_add_u64 v[20:21], s[50:51], 0, v[0:1]
	v_or_b32_e32 v0, 0x1800, v8
	v_lshl_add_u64 v[10:11], s[48:49], 0, v[8:9]
	v_lshl_add_u64 v[12:13], s[50:51], 0, v[8:9]
	v_lshl_add_u64 v[22:23], s[48:49], 0, v[0:1]
	v_lshl_add_u64 v[24:25], s[50:51], 0, v[0:1]
	v_or_b32_e32 v8, 0x1c00, v8
	v_and_b32_e32 v0, 63, v178
	s_add_u32 s0, s40, s0
	v_lshl_add_u64 v[26:27], s[48:49], 0, v[8:9]
	v_lshl_add_u64 v[28:29], s[50:51], 0, v[8:9]
	v_lshlrev_b32_e32 v8, 4, v0
	v_lshlrev_b32_e32 v0, 3, v0
	s_addc_u32 s1, s41, s1
	s_lshl_b64 s[6:7], s[28:29], 12
	v_lshl_add_u64 v[0:1], s[0:1], 0, v[0:1]
	s_mov_b64 s[0:1], 0xfc00800
	s_add_u32 s8, s40, s8
	s_movk_i32 s12, 0x1000
	v_lshl_add_u64 v[30:31], v[0:1], 0, s[0:1]
	s_addc_u32 s9, s41, s9
	s_mov_b32 s10, 0x3f9837f0
	s_mov_b32 s13, 0x17c01000
	v_mov_b32_e32 v58, 0x3727c5ac
	s_mov_b32 s14, 0xf800000
	v_mov_b32_e32 v59, 0x260
	global_load_dwordx4 v[114:117], v[10:11], off
	global_load_dwordx4 v[118:121], v[12:13], off
	global_load_dwordx4 v[122:125], v[10:11], off offset:1024
	global_load_dwordx4 v[126:129], v[12:13], off offset:1024
	global_load_dwordx4 v[130:133], v[10:11], off offset:2048
	global_load_dwordx4 v[134:137], v[12:13], off offset:2048
	global_load_dwordx4 v[138:141], v[10:11], off offset:3072
	global_load_dwordx4 v[142:145], v[12:13], off offset:3072
	global_load_dwordx4 v[146:149], v[14:15], off
	global_load_dwordx4 v[150:153], v[16:17], off
	global_load_dwordx4 v[154:157], v[14:15], off offset:1024
	global_load_dwordx4 v[158:161], v[16:17], off offset:1024
	global_load_dwordx4 v[162:165], v[14:15], off offset:2048
	global_load_dwordx4 v[166:169], v[16:17], off offset:2048
	global_load_dwordx4 v[170:173], v[14:15], off offset:3072
	global_load_dwordx4 v[174:177], v[16:17], off offset:3072
	s_waitcnt vmcnt(0)
.LBB0_611:
	v_lshl_add_u64 v[46:47], s[8:9], 0, v[8:9]
	v_add_co_u32_e64 v76, s[0:1], s13, v46
	global_load_dwordx2 v[32:33], v[30:31], off offset:-2048
	global_load_dwordx2 v[34:35], v[30:31], off offset:-1536
	global_load_dwordx2 v[36:37], v[30:31], off offset:-1024
	global_load_dwordx2 v[38:39], v[30:31], off offset:-512
	global_load_dwordx2 v[40:41], v[30:31], off
	v_add_co_u32_e32 v92, vcc, 0x17c00000, v46
	v_addc_co_u32_e64 v77, s[0:1], 0, v47, s[0:1]
	global_load_dwordx2 v[44:45], v[30:31], off offset:512
	global_load_dwordx2 v[48:49], v[30:31], off offset:1024
	global_load_dwordx2 v[50:51], v[30:31], off offset:1536
	global_load_dwordx4 v[60:63], v[76:77], off
	global_load_dwordx4 v[64:67], v[76:77], off offset:1024
	global_load_dwordx4 v[68:71], v[76:77], off offset:2048
	global_load_dwordx4 v[72:75], v[76:77], off offset:3072
	v_addc_co_u32_e32 v93, vcc, 0, v47, vcc
	global_load_dwordx4 v[76:79], v[92:93], off
	global_load_dwordx4 v[80:83], v[92:93], off offset:1024
	global_load_dwordx4 v[84:87], v[92:93], off offset:2048
	global_load_dwordx4 v[88:91], v[92:93], off offset:3072
	v_lshl_add_u64 v[42:43], s[2:3], 0, v[8:9]
	v_lshl_add_u64 v[30:31], v[30:31], 0, s[6:7]
	s_waitcnt vmcnt(15)
	v_lshlrev_b32_e32 v92, 16, v32
	v_and_b32_e32 v93, 0xffff0000, v32
	v_lshlrev_b32_e32 v94, 16, v33
	v_and_b32_e32 v95, 0xffff0000, v33
	s_waitcnt vmcnt(14)
	v_lshlrev_b32_e32 v96, 16, v34
	v_and_b32_e32 v97, 0xffff0000, v34
	v_lshlrev_b32_e32 v98, 16, v35
	v_and_b32_e32 v99, 0xffff0000, v35
	s_waitcnt vmcnt(13)
	v_lshlrev_b32_e32 v100, 16, v36
	v_and_b32_e32 v101, 0xffff0000, v36
	v_lshlrev_b32_e32 v102, 16, v37
	v_and_b32_e32 v103, 0xffff0000, v37
	s_waitcnt vmcnt(12)
	v_lshlrev_b32_e32 v104, 16, v38
	v_and_b32_e32 v105, 0xffff0000, v38
	v_lshlrev_b32_e32 v106, 16, v39
	v_and_b32_e32 v107, 0xffff0000, v39
	s_waitcnt vmcnt(11)
	v_lshlrev_b32_e32 v32, 16, v40
	v_and_b32_e32 v33, 0xffff0000, v40
	v_lshlrev_b32_e32 v34, 16, v41
	v_and_b32_e32 v35, 0xffff0000, v41
	s_waitcnt vmcnt(10)
	v_lshlrev_b32_e32 v36, 16, v44
	v_and_b32_e32 v37, 0xffff0000, v44
	v_lshlrev_b32_e32 v38, 16, v45
	v_and_b32_e32 v39, 0xffff0000, v45
	s_waitcnt vmcnt(9)
	v_lshlrev_b32_e32 v108, 16, v48
	v_and_b32_e32 v109, 0xffff0000, v48
	v_lshlrev_b32_e32 v110, 16, v49
	v_and_b32_e32 v111, 0xffff0000, v49
	s_waitcnt vmcnt(8)
; __global__ void __launch_bounds__(NTHREADS, 2) fwd_megakernel(Args args) {
;     ...
;         const float* row = HF + (size_t)m * DM; const bf16* mr = MIXB + (size_t)m * DM; f32x4 v[8]; float s = 0.f;
; #pragma unroll
;         for (int j = 0; j < 8; ++j) { const int c = 4 * (lane + 64 * j); const f32x4 hv = *(const f32x4*)(row + c); const v2u mv = *(const v2u*)(mr + c);
;             v[j] = hv * ALPHA + (f32x4){bflo(mv.x), bfhi(mv.x), bflo(mv.y), bfhi(mv.y)}; s += (v[j][0] + v[j][1]) + (v[j][2] + v[j][3]); }
;         const float mean = wave_sum(s) * (1.f / DM); float s2 = 0.f;
; #pragma unroll
;         for (int j = 0; j < 8; ++j) { v[j] = v[j] - mean; s2 += (v[j][0] * v[j][0] + v[j][1] * v[j][1]) + (v[j][2] * v[j][2] + v[j][3] * v[j][3]); }
	v_lshlrev_b32_e32 v112, 16, v50
	v_and_b32_e32 v113, 0xffff0000, v50
	v_lshlrev_b32_e32 v50, 16, v51
	v_and_b32_e32 v51, 0xffff0000, v51
	s_waitcnt vmcnt(7)
	v_pk_fma_f32 v[48:49], v[62:63], s[10:11], v[34:35] op_sel_hi:[1,0,1]
	v_pk_fma_f32 v[46:47], v[60:61], s[10:11], v[32:33] op_sel_hi:[1,0,1]
	s_waitcnt vmcnt(6)
	v_pk_fma_f32 v[40:41], v[64:65], s[10:11], v[36:37] op_sel_hi:[1,0,1]
	v_pk_fma_f32 v[44:45], v[66:67], s[10:11], v[38:39] op_sel_hi:[1,0,1]
	s_waitcnt vmcnt(5)
	v_pk_fma_f32 v[38:39], v[70:71], s[10:11], v[110:111] op_sel_hi:[1,0,1]
	v_pk_fma_f32 v[36:37], v[68:69], s[10:11], v[108:109] op_sel_hi:[1,0,1]
	s_waitcnt vmcnt(4)
	v_pk_fma_f32 v[34:35], v[74:75], s[10:11], v[50:51] op_sel_hi:[1,0,1]
	s_waitcnt vmcnt(3)
	v_pk_fma_f32 v[50:51], v[78:79], s[10:11], v[94:95] op_sel_hi:[1,0,1]
	v_pk_fma_f32 v[60:61], v[76:77], s[10:11], v[92:93] op_sel_hi:[1,0,1]
	s_waitcnt vmcnt(2)
	v_pk_fma_f32 v[62:63], v[82:83], s[10:11], v[98:99] op_sel_hi:[1,0,1]
	v_pk_fma_f32 v[64:65], v[80:81], s[10:11], v[96:97] op_sel_hi:[1,0,1]
	v_pk_fma_f32 v[32:33], v[72:73], s[10:11], v[112:113] op_sel_hi:[1,0,1]
	s_waitcnt vmcnt(1)
	v_pk_fma_f32 v[66:67], v[84:85], s[10:11], v[100:101] op_sel_hi:[1,0,1]
	v_pk_fma_f32 v[68:69], v[86:87], s[10:11], v[102:103] op_sel_hi:[1,0,1]
	s_waitcnt vmcnt(0)
	v_pk_fma_f32 v[70:71], v[90:91], s[10:11], v[106:107] op_sel_hi:[1,0,1]
	v_pk_fma_f32 v[72:73], v[88:89], s[10:11], v[104:105] op_sel_hi:[1,0,1]
	v_pk_mov_b32 v[80:81], v[40:41], v[44:45] op_sel:[1,0]
	v_mov_b32_e32 v82, v40
	v_mov_b32_e32 v83, v45
	v_add_f32_e32 v84, v36, v37
	v_add_f32_e32 v86, v38, v39
	v_mov_b32_e32 v85, v34
	v_mov_b32_e32 v87, v35
	v_mov_b32_e32 v88, v60
	v_mov_b32_e32 v89, v64
	v_mov_b32_e32 v90, v61
	v_mov_b32_e32 v91, v65
	v_mov_b32_e32 v92, v50
	v_mov_b32_e32 v93, v62
	v_mov_b32_e32 v94, v51
	v_mov_b32_e32 v95, v63
	v_mov_b32_e32 v77, v48
	v_mov_b32_e32 v79, v49
	v_pk_mov_b32 v[96:97], v[66:67], v[68:69] op_sel:[1,0]
	v_mov_b32_e32 v98, v66
	v_mov_b32_e32 v99, v69
	v_add_f32_e32 v76, v72, v73
	v_add_f32_e32 v78, v70, v71
	v_pk_add_f32 v[80:81], v[80:81], v[82:83]
	v_pk_add_f32 v[82:83], v[84:85], v[86:87]
	v_pk_add_f32 v[84:85], v[88:89], v[90:91]
	v_pk_add_f32 v[86:87], v[92:93], v[94:95]
	v_pk_add_f32 v[88:89], v[96:97], v[98:99]
	v_pk_add_f32 v[76:77], v[76:77], v[78:79]
	v_pk_add_f32 v[78:79], v[80:81], v[80:81] op_sel:[0,1] op_sel_hi:[1,0]
	v_pk_add_f32 v[80:81], v[84:85], v[86:87]
	v_pk_add_f32 v[84:85], v[88:89], v[88:89] op_sel:[0,1] op_sel_hi:[1,0]
	v_add_f32_e32 v74, 0, v80
	v_mov_b32_e32 v75, v46
	v_mov_b32_e32 v85, v47
	v_add_f32_e32 v74, v74, v81
	v_pk_add_f32 v[74:75], v[74:75], v[84:85]
	v_mov_b32_e32 v79, v33
	v_pk_add_f32 v[74:75], v[74:75], v[76:77]
	s_add_i32 s11, s11, s28
	v_pk_add_f32 v[74:75], v[74:75], v[74:75] op_sel:[0,1] op_sel_hi:[1,0]
	s_add_u32 s2, s2, s4
	v_mov_b32_e32 v75, v32
	v_pk_add_f32 v[74:75], v[74:75], v[78:79]
	s_addc_u32 s3, s3, s5
	v_pk_add_f32 v[74:75], v[74:75], v[82:83]
	s_add_u32 s8, s8, s4
	v_add_f32_e32 v74, v74, v75
	ds_bpermute_b32 v75, v52, v74
	s_addc_u32 s9, s9, s5
	s_cmpk_gt_i32 s11, 0x7fff
	s_waitcnt lgkmcnt(0)
	v_add_f32_e32 v74, v74, v75
	ds_bpermute_b32 v75, v53, v74
	s_waitcnt lgkmcnt(0)
	v_add_f32_e32 v74, v74, v75
	ds_bpermute_b32 v75, v54, v74
	s_waitcnt lgkmcnt(0)
	v_add_f32_e32 v74, v74, v75
	ds_bpermute_b32 v75, v55, v74
	s_waitcnt lgkmcnt(0)
	v_add_f32_e32 v74, v74, v75
	ds_bpermute_b32 v75, v56, v74
	s_waitcnt lgkmcnt(0)
	v_add_f32_e32 v74, v74, v75
	ds_bpermute_b32 v75, v57, v74
	s_waitcnt lgkmcnt(0)
	v_add_f32_e32 v74, v74, v75
	v_fmamk_f32 v51, v74, 0xba000000, v51
	v_fmamk_f32 v61, v74, 0xba000000, v61
	v_fmamk_f32 v63, v74, 0xba000000, v63
	v_fmamk_f32 v65, v74, 0xba000000, v65
	v_fmac_f32_e32 v50, 0xba000000, v74
	v_fmac_f32_e32 v60, 0xba000000, v74
	v_fmac_f32_e32 v62, 0xba000000, v74
	v_fmac_f32_e32 v64, 0xba000000, v74
	v_fmamk_f32 v67, v74, 0xba000000, v67
	v_fmac_f32_e32 v66, 0xba000000, v74
	v_fmamk_f32 v69, v74, 0xba000000, v69
	v_fmac_f32_e32 v68, 0xba000000, v74
	v_mov_b32_e32 v76, v61
	v_mov_b32_e32 v77, v65
	v_mov_b32_e32 v80, v51
	v_mov_b32_e32 v81, v63
	v_fmamk_f32 v73, v74, 0xba000000, v73
	v_fmac_f32_e32 v72, 0xba000000, v74
	v_fmamk_f32 v71, v74, 0xba000000, v71
	v_fmac_f32_e32 v70, 0xba000000, v74
	v_fmamk_f32 v49, v74, 0xba000000, v49
	v_fmac_f32_e32 v48, 0xba000000, v74
	v_fmamk_f32 v47, v74, 0xba000000, v47
	v_fmac_f32_e32 v46, 0xba000000, v74
	v_fmamk_f32 v41, v74, 0xba000000, v41
	v_fmac_f32_e32 v40, 0xba000000, v74
	v_fmamk_f32 v45, v74, 0xba000000, v45
	v_fmac_f32_e32 v44, 0xba000000, v74
	v_fmamk_f32 v37, v74, 0xba000000, v37
	v_fmac_f32_e32 v36, 0xba000000, v74
	v_fmamk_f32 v39, v74, 0xba000000, v39
	v_fmac_f32_e32 v38, 0xba000000, v74
	v_fmamk_f32 v35, v74, 0xba000000, v35
	v_fmac_f32_e32 v34, 0xba000000, v74
	v_fmamk_f32 v33, v74, 0xba000000, v33
	v_fmac_f32_e32 v32, 0xba000000, v74
	v_mov_b32_e32 v74, v60
	v_mov_b32_e32 v75, v64
	v_mov_b32_e32 v78, v50
	v_mov_b32_e32 v79, v62
	v_pk_mul_f32 v[82:83], v[68:69], v[68:69]
	v_pk_mul_f32 v[84:85], v[66:67], v[66:67]
	v_pk_mul_f32 v[76:77], v[76:77], v[76:77]
	v_pk_mul_f32 v[80:81], v[80:81], v[80:81]
	v_pk_mov_b32 v[98:99], v[84:85], v[82:83] op_sel:[1,0]
	v_mov_b32_e32 v85, v83
	v_pk_fma_f32 v[74:75], v[74:75], v[74:75], v[76:77]
	v_pk_fma_f32 v[76:77], v[78:79], v[78:79], v[80:81]
	v_mul_f32_e32 v86, v73, v73
	v_mul_f32_e32 v88, v71, v71
	v_pk_add_f32 v[78:79], v[98:99], v[84:85]
	v_pk_add_f32 v[74:75], v[74:75], v[76:77]
; __global__ void __launch_bounds__(NTHREADS, 2) fwd_megakernel(Args args) {
;     ...
;         const float mean = wave_sum(s) * (1.f / DM); float s2 = 0.f;
; #pragma unroll
;         for (int j = 0; j < 8; ++j) { v[j] = v[j] - mean; s2 += (v[j][0] * v[j][0] + v[j][1] * v[j][1]) + (v[j][2] * v[j][2] + v[j][3] * v[j][3]); }
;         const float rstd = 1.f / sqrtf(wave_sum(s2) * (1.f / DM) + LN_EPS);
; #pragma unroll
;         for (int j = 0; j < 8; ++j) { const int c = 4 * (lane + 64 * j); const f32x4 gg = *(const f32x4*)(ln2_g + c), bb = *(const f32x4*)(ln2_b + c);
;             __builtin_nontemporal_store(v[j] * rstd * gg + bb, (f32x4*)(args.out + (size_t)m * DM + c)); }
	v_mul_f32_e32 v97, v46, v46
	v_mul_f32_e32 v100, v47, v47
	v_mul_f32_e32 v101, v48, v48
	v_mul_f32_e32 v102, v49, v49
	v_pk_fma_f32 v[82:83], v[72:73], v[72:73], v[86:87] op_sel_hi:[1,1,0]
	v_pk_fma_f32 v[86:87], v[70:71], v[70:71], v[88:89] op_sel_hi:[1,1,0]
	v_pk_add_f32 v[76:77], v[78:79], v[78:79] op_sel:[0,1] op_sel_hi:[1,0]
	v_pk_add_f32 v[74:75], v[74:75], v[74:75] op_sel:[0,1] op_sel_hi:[1,0]
	v_pk_mul_f32 v[90:91], v[44:45], v[44:45]
	v_pk_mul_f32 v[92:93], v[40:41], v[40:41]
	v_mov_b32_e32 v83, v101
	v_mov_b32_e32 v87, v102
	v_mov_b32_e32 v77, v100
	v_mov_b32_e32 v75, v97
	v_pk_mov_b32 v[88:89], v[92:93], v[90:91] op_sel:[1,0]
	v_mov_b32_e32 v93, v91
	v_pk_add_f32 v[78:79], v[82:83], v[86:87]
	v_pk_add_f32 v[74:75], v[74:75], v[76:77]
	v_mul_f32_e32 v94, v37, v37
	v_mul_f32_e32 v96, v39, v39
	v_pk_add_f32 v[80:81], v[88:89], v[92:93]
	v_pk_add_f32 v[74:75], v[74:75], v[78:79]
	v_mul_f32_e32 v103, v32, v32
	v_mul_f32_e32 v104, v33, v33
	v_mul_f32_e32 v105, v34, v34
	v_mul_f32_e32 v106, v35, v35
	v_pk_fma_f32 v[90:91], v[36:37], v[36:37], v[94:95] op_sel_hi:[1,1,0]
	v_pk_fma_f32 v[94:95], v[38:39], v[38:39], v[96:97] op_sel_hi:[1,1,0]
	v_pk_add_f32 v[80:81], v[80:81], v[80:81] op_sel:[0,1] op_sel_hi:[1,0]
	v_pk_add_f32 v[74:75], v[74:75], v[74:75] op_sel:[0,1] op_sel_hi:[1,0]
	v_mov_b32_e32 v91, v105
	v_mov_b32_e32 v95, v106
	v_mov_b32_e32 v81, v104
	v_mov_b32_e32 v75, v103
	v_pk_add_f32 v[82:83], v[90:91], v[94:95]
	v_pk_add_f32 v[74:75], v[74:75], v[80:81]
	s_nop 0
	v_pk_add_f32 v[74:75], v[74:75], v[82:83]
	s_nop 0
	v_add_f32_e32 v74, v74, v75
	ds_bpermute_b32 v75, v52, v74
	s_waitcnt lgkmcnt(0)
	v_add_f32_e32 v74, v74, v75
	ds_bpermute_b32 v75, v53, v74
	s_waitcnt lgkmcnt(0)
	v_add_f32_e32 v74, v74, v75
	ds_bpermute_b32 v75, v54, v74
	s_waitcnt lgkmcnt(0)
	v_add_f32_e32 v74, v74, v75
	ds_bpermute_b32 v75, v55, v74
	s_waitcnt lgkmcnt(0)
	v_add_f32_e32 v74, v74, v75
	ds_bpermute_b32 v75, v56, v74
	s_waitcnt lgkmcnt(0)
	v_add_f32_e32 v74, v74, v75
	ds_bpermute_b32 v75, v57, v74
	s_waitcnt lgkmcnt(0)
	v_add_f32_e32 v74, v74, v75
	v_fmamk_f32 v74, v74, 0x3a000000, v58
	v_mul_f32_e32 v75, 0x4f800000, v74
	v_cmp_gt_f32_e32 vcc, s14, v74
	s_nop 1
	v_cndmask_b32_e32 v74, v74, v75, vcc
	v_sqrt_f32_e32 v75, v74
	s_nop 0
	v_add_u32_e32 v76, -1, v75
	v_add_u32_e32 v77, 1, v75
	v_fma_f32 v78, -v76, v75, v74
	v_fma_f32 v79, -v77, v75, v74
	v_cmp_ge_f32_e64 s[0:1], 0, v78
	s_nop 1
	v_cndmask_b32_e64 v75, v75, v76, s[0:1]
	v_cmp_lt_f32_e64 s[0:1], 0, v79
	s_nop 1
	v_cndmask_b32_e64 v75, v75, v77, s[0:1]
	v_mul_f32_e32 v76, 0x37800000, v75
	v_cndmask_b32_e32 v75, v75, v76, vcc
	v_cmp_class_f32_e32 vcc, v74, v59
	s_nop 1
	v_cndmask_b32_e32 v74, v75, v74, vcc
	v_div_scale_f32 v75, s[0:1], v74, v74, 1.0
	v_rcp_f32_e32 v77, v75
	v_div_scale_f32 v76, vcc, 1.0, v74, 1.0
	v_fma_f32 v78, -v75, v77, 1.0
	v_fmac_f32_e32 v77, v78, v77
	v_mul_f32_e32 v78, v76, v77
	v_fma_f32 v79, -v75, v78, v76
	v_fmac_f32_e32 v78, v79, v77
	v_fma_f32 v75, -v75, v78, v76
	v_div_fmas_f32 v75, v75, v77, v78
	v_div_fixup_f32 v74, v75, v74, 1.0
	v_pk_mul_f32 v[60:61], v[74:75], v[60:61] op_sel_hi:[0,1]
	v_pk_mul_f32 v[50:51], v[74:75], v[50:51] op_sel_hi:[0,1]
	v_pk_fma_f32 v[2:3], v[116:117], v[50:51], v[120:121]
	v_pk_fma_f32 v[0:1], v[114:115], v[60:61], v[118:119]
	global_store_dwordx4 v[42:43], v[0:3], off nt
	v_pk_mul_f32 v[50:51], v[74:75], v[62:63] op_sel_hi:[0,1]
	v_pk_mul_f32 v[60:61], v[74:75], v[64:65] op_sel_hi:[0,1]
	v_pk_mul_f32 v[48:49], v[74:75], v[48:49] op_sel_hi:[0,1]
	v_pk_mul_f32 v[46:47], v[74:75], v[46:47] op_sel_hi:[0,1]
	v_pk_mul_f32 v[44:45], v[74:75], v[44:45] op_sel_hi:[0,1]
	v_pk_mul_f32 v[40:41], v[74:75], v[40:41] op_sel_hi:[0,1]
	v_pk_mul_f32 v[38:39], v[74:75], v[38:39] op_sel_hi:[0,1]
	v_pk_mul_f32 v[36:37], v[74:75], v[36:37] op_sel_hi:[0,1]
	v_pk_mul_f32 v[34:35], v[74:75], v[34:35] op_sel_hi:[0,1]
	v_pk_mul_f32 v[32:33], v[74:75], v[32:33] op_sel_hi:[0,1]
	v_pk_fma_f32 v[4:5], v[122:123], v[60:61], v[126:127]
	v_pk_fma_f32 v[6:7], v[124:125], v[50:51], v[128:129]
	global_store_dwordx4 v[42:43], v[4:7], off offset:1024 nt
	v_pk_mul_f32 v[50:51], v[74:75], v[68:69] op_sel_hi:[0,1]
	v_pk_mul_f32 v[60:61], v[74:75], v[66:67] op_sel_hi:[0,1]
	v_pk_fma_f32 v[0:1], v[130:131], v[60:61], v[134:135]
	v_pk_fma_f32 v[2:3], v[132:133], v[50:51], v[136:137]
	global_store_dwordx4 v[42:43], v[0:3], off offset:2048 nt
	v_pk_mul_f32 v[50:51], v[74:75], v[70:71] op_sel_hi:[0,1]
	v_pk_mul_f32 v[60:61], v[74:75], v[72:73] op_sel_hi:[0,1]
	v_pk_fma_f32 v[4:5], v[138:139], v[60:61], v[142:143]
	v_pk_fma_f32 v[6:7], v[140:141], v[50:51], v[144:145]
	global_store_dwordx4 v[42:43], v[4:7], off offset:3072 nt
	v_add_co_u32_e32 v42, vcc, s12, v42
	v_pk_fma_f32 v[0:1], v[146:147], v[46:47], v[150:151]
	v_addc_co_u32_e32 v43, vcc, 0, v43, vcc
	v_pk_fma_f32 v[2:3], v[148:149], v[48:49], v[152:153]
	global_store_dwordx4 v[42:43], v[0:3], off nt
	v_pk_fma_f32 v[4:5], v[154:155], v[40:41], v[158:159]
	v_pk_fma_f32 v[6:7], v[156:157], v[44:45], v[160:161]
	global_store_dwordx4 v[42:43], v[4:7], off offset:1024 nt
	v_pk_fma_f32 v[0:1], v[162:163], v[36:37], v[166:167]
	v_pk_fma_f32 v[2:3], v[164:165], v[38:39], v[168:169]
	global_store_dwordx4 v[42:43], v[0:3], off offset:2048 nt
	v_pk_fma_f32 v[4:5], v[170:171], v[32:33], v[174:175]
	v_pk_fma_f32 v[6:7], v[172:173], v[34:35], v[176:177]
	global_store_dwordx4 v[42:43], v[4:7], off offset:3072 nt
	s_cbranch_scc0 .LBB0_611
